# prep_weights: each matrix's item loop starts where the previous matrix stopped (global round-robin over waves) instead of every matrix starting at wave 0
# speedup vs baseline: 1.0072x; 1.0072x over previous
; __device__ __forceinline__ int otid() { int t = threadIdx.x; asm volatile("" : "+v"(t)); return t; }
; __device__ __forceinline__ void prep_weights(lptr L, const Params& P, int l) {
;     const int tid = otid(), lane = tid & 63, wave = tid >> 6;
;     const int gw = blockIdx.x * 8 + wave, NGW = gridDim.x * 8;
;     const lptr scr = L + wave * 8704;
;     unsigned char* ws = P.ws;
; #pragma unroll 1
;     for (int mi = 0; mi < 14; ++mi) {
;         const float* W; int K, N, mode = 0; bf16_t* WT;
.LBB0_880:
	s_andn2_b64 vcc, exec, s[2:3]
	s_cbranch_vccnz .LBB0_941
	s_cmp_lg_u32 s76, 0
	s_cbranch_scc1 .LBB0_941
	v_mov_b32_e32 v13, v193
	v_readlane_b32 s0, v252, 40
	v_bfe_u32 v19, v13, 3, 3
	v_lshlrev_b32_e32 v0, 2, v13
	v_and_b32_e32 v0, 28, v0
	v_mul_u32_u24_e32 v2, 33, v19
	v_add_lshl_u32 v20, v2, v0, 2
	v_lshlrev_b32_e32 v2, 3, v13
	v_and_b32_e32 v2, 56, v2
	v_ashrrev_i32_e32 v3, 6, v13
	v_mul_u32_u24_e32 v6, 33, v2
	v_add_u32_e32 v15, s0, v3
	s_movk_i32 s0, 0x2200
	v_or_b32_e32 v21, 8, v19
	v_or_b32_e32 v22, 16, v19
	v_or_b32_e32 v23, 24, v19
	v_or_b32_e32 v8, v6, v19
	v_mul_lo_u32 v18, v3, s0
	v_add_u32_e32 v4, 0x420, v20
	v_add_u32_e32 v5, 0x840, v20
	v_add_u32_e32 v7, 0xc60, v20
	v_lshlrev_b32_e32 v8, 2, v8
	v_add_lshl_u32 v9, v6, v21, 2
	v_add_lshl_u32 v10, v6, v22, 2
	v_add_lshl_u32 v11, v6, v23, 2
	v_readlane_b32 s0, v255, 7
	s_mov_b32 s5, 0
	s_mov_b32 s99, 0
	v_lshlrev_b32_e32 v0, 2, v0
	v_lshl_add_u32 v24, v3, 5, s0
	v_lshlrev_b32_e32 v6, 1, v2
	v_add_u32_e32 v25, v18, v4
	v_add_u32_e32 v26, v18, v5
	v_add_u32_e32 v27, v18, v7
	v_add_u32_e32 v28, v18, v8
	v_add_u32_e32 v29, v18, v9
	v_add_u32_e32 v30, v18, v10
	v_add_u32_e32 v31, v18, v11
	s_branch .LBB0_884

; __device__ __forceinline__ void prep_weights(lptr L, const Params& P, int l) {
;     ...
;         const int nblk = N / 32, nitems = (K / 64) * nblk;
;         for (int it = gw; it < nitems; it += NGW) {
;             const int kb = it / nblk, nb = it - kb * nblk, n0 = 32 * nb;
.LBB0_932:
	s_lshr_b32 s14, s10, 5
	s_lshr_b32 s18, s13, 6
	s_mul_i32 s18, s18, s14
	s_add_i32 s30, s55, -1
	v_subrev_u32_e32 v14, s99, v15
	v_and_b32_e32 v14, s30, v14
	s_add_i32 s99, s99, s18
	v_cmp_gt_i32_e32 vcc, s18, v14
	s_and_saveexec_b64 s[2:3], vcc
	s_cbranch_execz .LBB0_883
	v_cvt_f32_u32_e32 v2, s14
	v_mov_b32_e32 v7, v1
	v_lshl_add_u64 v[10:11], s[26:27], 0, v[6:7]
	s_sub_i32 s26, 0, s14
	v_rcp_iflag_f32_e32 v2, v2
	v_lshl_add_u64 v[8:9], s[6:7], 0, v[0:1]
	s_lshl_b32 s6, s14, 5
	s_sub_i32 s27, 0, s6
	v_mul_f32_e32 v2, 0x4f7ffffe, v2
	v_cvt_u32_f32_e32 v2, v2
	s_mov_b64 s[6:7], 0
	v_lshlrev_b32_e32 v12, 5, v14
	v_mul_lo_u32 v3, s26, v2
	v_mul_hi_u32 v3, v2, v3
	v_add_u32_e32 v7, v2, v3
	s_branch .LBB0_935
